# norm phases: xor-8/2/1 stages of the wave sum done with DPP adds (row_ror:8, quad_perm) instead of ds_bpermute round trips, same butterfly order
# speedup vs baseline: 1.0017x; 1.0017x over previous
; __device__ __forceinline__ unsigned pack2(float a, float b) { unsigned r; asm("s_nop 1\n\tv_cvt_pk_bf16_f32 %0, %1, %2" : "=v"(r) : "v"(a), "v"(b)); return r; }
; __device__ __forceinline__ float* wsMOD(const Params& p) { return (float*)(p.ws + OFF_MOD); }
; __device__ __forceinline__ void norm_phase(const Params& p, int layer, int which, int first) {
;     ...
;   for (int row = blockIdx.x * 8 + wave; row < TALL; row += gridDim.x * 8) {
;     int b = row / SALL; int pp = row - b * SALL; bool ctx = pp < NCTX;
;     float* xr = xrow_ptr(p, row);
;     const float* src = first ? (ctx ? p.in[2] + (size_t)(b * NCTX + pp) * DM : p.in[0] + (size_t)(b * 8192 + pp - NCTX) * DM) : xr;
;     float4 v[4]; float ss = 0;
; #pragma unroll
;     for (int i = 0; i < 4; ++i) { v[i] = *(const float4*)(src + lane * 4 + i * 256); ss += v[i].x * v[i].x + v[i].y * v[i].y + v[i].z * v[i].z + v[i].w * v[i].w; }
;     ss = wave_sum(ss);
;     float rstd = rsqrtf(ss * (1.f / 1024.f) + 1e-6f);
;     const float* mod = wsMOD(p) + (size_t)(layer * 9 + (ctx ? 8 : b)) * 6144 + (which ? 3 : 0) * 1024;
; #pragma unroll
;     for (int i = 0; i < 4; ++i) {
;       int col = lane * 4 + i * 256;
;       float4 gg = *(const float4*)(g + col), sh = *(const float4*)(mod + col), sc = *(const float4*)(mod + 1024 + col);
;       float h0 = v[i].x * rstd * gg.x * (1.f + sc.x) + sh.x, h1 = v[i].y * rstd * gg.y * (1.f + sc.y) + sh.y;
;       float h2 = v[i].z * rstd * gg.z * (1.f + sc.z) + sh.z, h3 = v[i].w * rstd * gg.w * (1.f + sc.w) + sh.w;
;       uint2 pk; pk.x = pack2(h0, h1); pk.y = pack2(h2, h3);
;       *(uint2*)(H + (size_t)row * DM + col) = pk;
;       if (first && ctx) *(float4*)(xr + col) = v[i];
.LBB0_1008:
	v_lshlrev_b32_e32 v160, 2, v22
	v_lshl_add_u64 v[0:1], v[0:1], 0, v[160:161]
	global_load_dwordx4 v[12:15], v[0:1], off
	global_load_dwordx4 v[8:11], v[0:1], off offset:1024
	global_load_dwordx4 v[4:7], v[0:1], off offset:2048
	s_nop 0
	global_load_dwordx4 v[0:3], v[0:1], off offset:3072
	global_load_dwordx4 v[48:51], v[24:25], off
	s_mov_b32 s7, 0x800000
	v_cndmask_b32_e64 v16, v16, 8, s[40:41]
	v_add_u32_e32 v16, s2, v16
	s_mov_b64 s[36:37], 0x1000
	v_mul_hi_i32_i24_e32 v17, 0x6000, v16
	v_mul_i32_i24_e32 v16, 0x6000, v16
	v_lshl_add_u64 v[16:17], s[30:31], 0, v[16:17]
	v_lshl_add_u64 v[36:37], v[16:17], 0, s[36:37]
	v_lshl_add_u64 v[38:39], v[16:17], 0, v[160:161]
	v_lshl_add_u64 v[106:107], v[36:37], 0, v[160:161]
	global_load_dwordx4 v[60:63], v[38:39], off
	v_mov_b32_e32 v29, v161
	global_load_dwordx4 v[52:55], v[106:107], off
	v_lshl_add_u64 v[100:101], v[36:37], 0, v[28:29]
	global_load_dwordx4 v[64:67], v[24:25], off offset:1024
	v_mov_b32_e32 v31, v161
	global_load_dwordx4 v[68:71], v[100:101], off
	v_lshl_add_u64 v[102:103], v[36:37], 0, v[30:31]
	global_load_dwordx4 v[72:75], v[38:39], off offset:1024
	v_mov_b32_e32 v33, v161
	global_load_dwordx4 v[76:79], v[24:25], off offset:2048
	v_lshl_add_u64 v[104:105], v[36:37], 0, v[32:33]
	global_load_dwordx4 v[80:83], v[38:39], off offset:2048
	global_load_dwordx4 v[84:87], v[102:103], off
	global_load_dwordx4 v[88:91], v[24:25], off offset:3072
	global_load_dwordx4 v[92:95], v[38:39], off offset:3072
	global_load_dwordx4 v[96:99], v[104:105], off
	v_ashrrev_i32_e32 v21, 31, v20
	v_lshlrev_b64 v[40:41], 11, v[20:21]
	s_and_b64 s[36:37], s[26:27], s[40:41]
	s_waitcnt vmcnt(15)
	v_mov_b32_e32 v56, v13
	s_waitcnt vmcnt(14)
	v_mov_b32_e32 v57, v9
	v_mov_b32_e32 v58, v12
	v_mov_b32_e32 v59, v8
	v_pk_mul_f32 v[56:57], v[56:57], v[56:57]
	s_nop 0
	v_pk_fma_f32 v[58:59], v[58:59], v[58:59], v[56:57]
	v_mov_b32_e32 v56, v14
	v_mov_b32_e32 v57, v10
	v_pk_fma_f32 v[58:59], v[56:57], v[56:57], v[58:59]
	v_mov_b32_e32 v56, v15
	v_mov_b32_e32 v57, v11
	v_pk_fma_f32 v[18:19], v[56:57], v[56:57], v[58:59]
	s_waitcnt vmcnt(13)
	v_mov_b32_e32 v56, v5
	s_waitcnt vmcnt(12)
	v_mov_b32_e32 v57, v1
	v_add_f32_e32 v17, v18, v19
	v_mov_b32_e32 v58, v4
	v_mov_b32_e32 v59, v0
	v_pk_mul_f32 v[56:57], v[56:57], v[56:57]
	s_nop 0
	v_pk_fma_f32 v[58:59], v[58:59], v[58:59], v[56:57]
	v_mov_b32_e32 v56, v6
	v_mov_b32_e32 v57, v2
	v_pk_fma_f32 v[58:59], v[56:57], v[56:57], v[58:59]
	v_mov_b32_e32 v56, v7
	v_mov_b32_e32 v57, v3
	v_pk_fma_f32 v[58:59], v[56:57], v[56:57], v[58:59]
	s_nop 0
	v_add_f32_e32 v17, v17, v58
	v_add_f32_e32 v17, v17, v59
	ds_bpermute_b32 v18, v23, v17
	s_waitcnt lgkmcnt(0)
	v_add_f32_e32 v17, v17, v18
	ds_bpermute_b32 v18, v42, v17
	s_waitcnt lgkmcnt(0)
	v_add_f32_e32 v17, v17, v18
	s_nop 1
	v_add_f32_dpp v17, v17, v17 row_ror:8 row_mask:0xf bank_mask:0xf bound_ctrl:1
	ds_bpermute_b32 v18, v44, v17
	s_waitcnt lgkmcnt(0)
	v_add_f32_e32 v17, v17, v18
	s_nop 1
	v_add_f32_dpp v17, v17, v17 quad_perm:[2,3,0,1] row_mask:0xf bank_mask:0xf bound_ctrl:1
	s_nop 1
	v_add_f32_dpp v17, v17, v17 quad_perm:[1,0,3,2] row_mask:0xf bank_mask:0xf bound_ctrl:1
	v_fmamk_f32 v17, v17, 0x3a800000, v162
	v_cmp_gt_f32_e32 vcc, s7, v17
	v_mul_f32_e32 v18, 0x4b800000, v17
	s_nop 0
	v_cndmask_b32_e32 v17, v17, v18, vcc
	v_rsq_f32_e32 v17, v17
	s_nop 0
	v_mul_f32_e32 v18, 0x45800000, v17
	v_cndmask_b32_e32 v47, v17, v18, vcc
	v_mul_f32_e32 v21, v12, v47
	s_waitcnt vmcnt(9)
	v_mul_f32_e32 v21, v48, v21
	v_add_f32_e32 v29, 1.0, v52
	v_fma_f32 v16, v29, v21, v60
	v_mul_f32_e32 v21, v13, v47
	v_mul_f32_e32 v21, v49, v21
	v_add_f32_e32 v29, 1.0, v53
	v_fma_f32 v17, v29, v21, v61
	v_mul_f32_e32 v21, v14, v47
	v_mul_f32_e32 v21, v50, v21
	v_add_f32_e32 v29, 1.0, v54
	v_fma_f32 v21, v29, v21, v62
	v_mul_f32_e32 v18, v15, v47
	v_mul_f32_e32 v18, v51, v18
	v_add_f32_e32 v29, 1.0, v55
	v_fmac_f32_e32 v63, v18, v29
	s_nop 1
	v_cvt_pk_bf16_f32 v18, v16, v17
	v_lshl_add_u64 v[16:17], v[26:27], 0, v[40:41]
	s_nop 1
	v_cvt_pk_bf16_f32 v19, v21, v63
	global_store_dwordx2 v[16:17], v[18:19], off
	s_and_saveexec_b64 s[38:39], s[36:37]
	s_cbranch_execz .LBB0_1010
	v_lshl_add_u64 v[56:57], v[34:35], 0, v[160:161]
	global_store_dwordx4 v[56:57], v[12:15], off
